# NC=32: latent-chain workgroups convert no PEER table items in the layer-0 scan phase (context workgroups take all 32)
# speedup vs baseline: 1.0002x; 1.0002x over previous
.LBB0_226:
	v_readlane_b32 s4, v253, 0
	s_and_b32 s33, s4, 7
	s_mov_b64 s[6:7], s[80:81]
	s_xor_b32 s2, s33, 7
	s_add_i32 s2, s6, s2
	s_lshr_b32 s83, s2, 3
	s_cmpk_lt_u32 s4, 0xf00
	s_cselect_b64 s[2:3], -1, 0
	v_readlane_b32 s5, v253, 1
	v_writelane_b32 v253, s2, 22
	s_mul_i32 s1, s7, s6
	s_mul_i32 s97, s1, s0
	v_writelane_b32 v253, s3, 23
	s_lshr_b32 s2, s4, 3
	v_writelane_b32 v253, s2, 24
	s_lshl_b32 s2, s33, 7
	s_add_u32 s0, s68, 0x38e00200
	v_writelane_b32 v253, s2, 25
	s_addc_u32 s1, s69, 0
	v_writelane_b32 v253, s0, 26
	v_lshrrev_b32_e32 v1, 20, v0
	v_lshrrev_b32_e32 v0, 10, v0
	v_writelane_b32 v253, s1, 27
	s_add_u32 s0, s68, 0x38e00400
	s_addc_u32 s1, s69, 0
	v_writelane_b32 v253, s0, 18
	v_or_b32_e32 v0, v0, v1
	s_mov_b32 s81, 0
	v_writelane_b32 v253, s1, 19
	s_add_u32 s0, s68, 0x38e00500
	s_addc_u32 s1, s69, 0
	v_writelane_b32 v253, s0, 10
	s_mov_b32 s7, s81
	s_mov_b32 s30, 2
	v_writelane_b32 v253, s1, 11
	s_add_u32 s0, s68, 0x38e00600
	s_addc_u32 s1, s69, 0
	v_writelane_b32 v253, s0, 12
	s_movk_i32 s89, 0xff00
	s_movk_i32 s91, 0xff
	v_writelane_b32 v253, s1, 13
	s_add_u32 s0, s68, 0x38e00700
	s_addc_u32 s1, s69, 0
	v_writelane_b32 v253, s0, 14
	v_mov_b32_e32 v129, 0
	s_mov_b64 s[40:41], 0
	v_writelane_b32 v253, s1, 15
	s_add_u32 s0, s68, 0x38e00800
	s_addc_u32 s1, s69, 0
	v_writelane_b32 v253, s0, 16
	s_mov_b64 s[86:87], 0x1a00080
	s_mov_b64 s[36:37], 0xa3ff000
	v_writelane_b32 v253, s1, 17
	s_add_u32 s0, s68, 0x38e00900
	s_addc_u32 s1, s69, 0
	v_writelane_b32 v253, s0, 28
	v_mov_b32_e32 v178, 0x12004
	v_mov_b32_e32 v179, 1
	v_writelane_b32 v253, s1, 29
	s_add_u32 s0, s68, 0x38e00a00
	s_addc_u32 s1, s69, 0
	v_writelane_b32 v253, s0, 30
	s_mov_b32 s88, 0x3e38aa3b
	s_movk_i32 s10, 0x1f8
	v_writelane_b32 v253, s1, 31
	s_add_u32 s0, s68, 0x38e00b00
	s_addc_u32 s1, s69, 0
	v_writelane_b32 v253, s0, 32
	s_brev_b32 s11, -2
	s_brev_b32 s12, 18
	v_writelane_b32 v253, s1, 33
	s_add_u32 s0, s68, 0x38e00c00
	s_addc_u32 s1, s69, 0
	v_writelane_b32 v253, s0, 34
	s_mov_b32 s13, 0x800000
	s_brev_b32 s14, 1
	v_writelane_b32 v253, s1, 35
	s_add_u32 s0, s68, 0x38e00d00
	s_addc_u32 s1, s69, 0
	v_writelane_b32 v253, s0, 36
	v_mov_b32_e32 v180, 0x3c0881c4
	v_mov_b32_e32 v181, 0xbab64f3b
	v_writelane_b32 v253, s1, 37
	s_add_u32 s0, s68, 0x38e00e00
	s_addc_u32 s1, s69, 0
	v_writelane_b32 v253, s0, 38
	s_mov_b32 s15, 0x3e800000
	s_mov_b32 s16, 0x3f400000
	v_writelane_b32 v253, s1, 39
	s_add_u32 s0, s68, 0x38e00f00
	s_addc_u32 s1, s69, 0
	v_writelane_b32 v253, s0, 40
	s_mov_b32 s17, 0x3fa00000
	s_mov_b32 s18, 0x3fe00000
	v_writelane_b32 v253, s1, 41
	s_add_u32 s0, s68, 0x38e01000
	s_addc_u32 s1, s69, 0
	v_writelane_b32 v253, s0, 42
	s_mov_b32 s19, 0x40200000
	s_mov_b32 s20, 0x40600000
	v_writelane_b32 v253, s1, 43
	s_add_u32 s0, s68, 0x38e01100
	s_addc_u32 s1, s69, 0
	v_writelane_b32 v253, s0, 44
	s_mov_b32 s21, 0x40a00000
	s_movk_i32 s22, 0x1fff
	v_writelane_b32 v253, s1, 45
	s_add_u32 s0, s68, 0x38e01200
	s_addc_u32 s1, s69, 0
	v_writelane_b32 v253, s0, 46
	s_movk_i32 s23, 0x6000
	s_mov_b32 s24, 0xa000
	v_writelane_b32 v253, s1, 47
	s_add_u32 s0, s68, 0x38e01300
	s_addc_u32 s1, s69, 0
	v_writelane_b32 v253, s0, 48
	s_cmp_eq_u32 s63, 15
	s_mov_b32 s25, 0x13600000
	v_writelane_b32 v253, s1, 49
	s_cselect_b64 s[0:1], -1, 0
	v_writelane_b32 v253, s0, 50
	s_cmp_eq_u32 s63, 14
	s_mov_b32 s26, 0x9fff
	v_writelane_b32 v253, s1, 51
	s_cselect_b64 s[0:1], -1, 0
	v_writelane_b32 v253, s0, 52
	s_cmp_eq_u32 s63, 13
	v_mov_b32_e32 v182, 0x3727c5ac
	v_writelane_b32 v253, s1, 53
	s_cselect_b64 s[0:1], -1, 0
	v_writelane_b32 v253, s0, 54
	s_cmp_eq_u32 s63, 12
	s_movk_i32 s28, 0x7f
	v_writelane_b32 v253, s1, 55
	s_cselect_b64 s[0:1], -1, 0
	v_writelane_b32 v253, s0, 56
	s_cmp_eq_u32 s63, 11
	s_movk_i32 s29, 0x7f00
	v_writelane_b32 v253, s1, 57
	s_cselect_b64 s[0:1], -1, 0
	v_writelane_b32 v253, s0, 58
	s_cmp_eq_u32 s63, 10
	v_mov_b32_e32 v183, 0x7f
	v_writelane_b32 v253, s1, 59
	s_cselect_b64 s[0:1], -1, 0
	v_writelane_b32 v253, s0, 60
	s_cmp_eq_u32 s63, 9
	v_mov_b32_e32 v184, 0x7d
	v_writelane_b32 v253, s1, 61
	s_cselect_b64 s[0:1], -1, 0
	v_writelane_b32 v253, s0, 62
	s_cmp_eq_u32 s63, 8
	s_mov_b32 s82, 0x41d00000
	v_writelane_b32 v253, s1, 63
	s_cselect_b64 s[0:1], -1, 0
	v_writelane_b32 v254, s0, 0
	s_cmp_eq_u32 s63, 7
	v_mov_b32_e32 v185, 0x7b
	v_writelane_b32 v254, s1, 1
	s_cselect_b64 s[0:1], -1, 0
	v_writelane_b32 v254, s0, 2
	s_cmp_eq_u32 s63, 6
	v_mov_b32_e32 v186, 0x79
	v_writelane_b32 v254, s1, 3
	s_cselect_b64 s[0:1], -1, 0
	v_writelane_b32 v254, s0, 4
	s_cmp_eq_u32 s63, 5
	s_mov_b32 s90, 0x3d1d89d9
	v_writelane_b32 v254, s1, 5
	s_cselect_b64 s[0:1], -1, 0
	v_writelane_b32 v254, s0, 6
	s_cmp_eq_u32 s63, 4
	v_not_b32_e32 v187, 63
	v_writelane_b32 v254, s1, 7
	s_cselect_b64 s[0:1], -1, 0
	v_writelane_b32 v254, s0, 8
	s_cmp_eq_u32 s63, 3
	v_mov_b32_e32 v189, 0xf149f2ca
	v_writelane_b32 v254, s1, 9
	s_cselect_b64 s[0:1], -1, 0
	v_writelane_b32 v254, s0, 10
	s_cmp_eq_u32 s63, 2
	v_not_b32_e32 v190, 31
	v_writelane_b32 v254, s1, 11
	s_cselect_b64 s[0:1], -1, 0
	v_writelane_b32 v254, s0, 12
	s_cmp_eq_u32 s63, 1
	v_mov_b32_e32 v191, 0x7fc00000
	v_writelane_b32 v254, s1, 13
	s_cselect_b64 s[0:1], -1, 0
	v_writelane_b32 v254, s0, 14
	s_cmp_eq_u32 s63, 0
	s_nop 0
	v_writelane_b32 v254, s1, 15
	s_cselect_b64 s[0:1], -1, 0
	v_writelane_b32 v254, s0, 16
	s_nop 1
	v_writelane_b32 v254, s1, 17
	s_lshl_b32 s0, s63, 8
	s_add_u32 s0, s76, s0
	s_addc_u32 s1, s77, 0
	s_add_u32 s2, s0, 0x1400
	s_addc_u32 s3, s1, 0
	v_writelane_b32 v254, s2, 18
	s_add_u32 s0, s0, 0x2400
	s_addc_u32 s1, s1, 0
	v_writelane_b32 v254, s3, 19
	v_writelane_b32 v254, s0, 20
	s_nop 1
	v_writelane_b32 v254, s1, 21
	s_add_u32 s0, s68, 0x38e03400
	s_addc_u32 s1, s69, 0
	v_writelane_b32 v254, s0, 22
	s_nop 1
	v_writelane_b32 v254, s1, 23
	s_add_u32 s0, s68, 0x38e03500
	s_addc_u32 s1, s69, 0
	v_writelane_b32 v254, s0, 24
	s_cmpk_lt_i32 s4, 0x1400
	s_mov_b64 s[68:69], 0xb3fec00
	v_writelane_b32 v254, s1, 25
	s_movk_i32 s0, 0x3ff
	v_and_or_b32 v0, v0, s0, v133
	v_cmp_eq_u32_e64 s[0:1], 0, v0
	v_mov_b32_e32 v0, 0x100
	v_sub_co_u32_e32 v0, vcc, s4, v0
	v_writelane_b32 v254, s0, 26
	s_nop 1
	v_writelane_b32 v254, s1, 27
	s_cselect_b64 s[0:1], -1, 0
	v_writelane_b32 v254, s0, 28
	s_cmpk_lt_u32 s4, 0xa00
	s_nop 0
	v_writelane_b32 v254, s1, 29
	s_cselect_b64 s[0:1], -1, 0
	v_writelane_b32 v254, s0, 30
	s_add_i32 s2, s6, 0xffffff00
	s_nop 0
	v_writelane_b32 v254, s1, 31
	s_and_b64 s[0:1], vcc, exec
	v_writelane_b32 v254, s2, 32
	s_cselect_b32 s0, 0x100000, s2
	s_cmpk_gt_u32 s6, 0x13f
	v_readfirstlane_b32 s1, v0
	s_cselect_b32 s0, s0, s6
	s_add_i32 s98, s4, 0x2000
	s_cmpk_lt_u32 s4, 0x100
	s_cselect_b32 s98, s98, s1
	s_cmpk_eq_u32 s6, 0x200
	s_cselect_b32 s1, s98, s1
	s_cselect_b64 s[98:99], -1, 0
	s_cmpk_lt_i32 s4, 0x500
	v_writelane_b32 v254, s1, 33
	v_writelane_b32 v254, s0, 34
	s_cselect_b64 s[0:1], -1, 0
	v_writelane_b32 v254, s0, 35
	s_cmpk_gt_u32 s6, 0x1ff
	s_nop 0
	v_writelane_b32 v254, s1, 36
	s_cselect_b64 s[0:1], -1, 0
	s_cmpk_gt_u32 s4, 0xff
	s_cselect_b64 s[2:3], -1, 0
	s_and_b64 s[0:1], s[2:3], s[0:1]
	s_cmpk_lt_i32 s4, 0x2100
	s_cselect_b64 s[2:3], -1, 0
	s_and_b64 s[0:1], s[2:3], s[0:1]
	s_lshl_b64 s[76:77], s[6:7], 8
	s_or_b64 s[0:1], s[0:1], s[98:99]
	v_writelane_b32 v254, s0, 37
	s_cmpk_lt_u32 s4, 0x1400
	v_readlane_b32 s2, v253, 20
	v_writelane_b32 v254, s1, 38
	s_cselect_b64 s[0:1], -1, 0
	v_writelane_b32 v254, s0, 39
	s_lshl_b32 s84, s6, 2
	v_readlane_b32 s3, v253, 21
	v_writelane_b32 v254, s1, 40
	s_bfe_i32 s0, s6, 0x1001d
	v_writelane_b32 v254, s0, 41
	s_abs_i32 s0, s84
	v_cvt_f32_u32_e32 v0, s0
	v_writelane_b32 v254, s0, 42
	s_sub_i32 s0, 0, s0
	s_lshl_b64 s[8:9], s[2:3], 4
	v_rcp_iflag_f32_e32 v0, v0
	s_lshl_b32 s1, s33, 18
	s_lshl_b32 s5, s4, 2
	s_mov_b64 s[34:35], s[76:77]
	v_mul_f32_e32 v0, 0x4f7ffffe, v0
	v_cvt_u32_f32_e32 v0, v0
	v_mul_lo_u32 v1, s0, v0
	v_readlane_b32 s0, v254, 33
	s_lshl_b32 s0, s0, 13
	v_writelane_b32 v254, s0, 43
	s_lshl_b32 s0, s6, 13
	s_add_i32 s0, s0, 0xffe00000
	v_writelane_b32 v254, s0, 44
	v_writelane_b32 v254, s8, 45
	s_mov_b32 s0, s6
	v_mul_hi_u32 v1, v0, v1
	v_writelane_b32 v254, s9, 46
	s_lshl_b64 s[8:9], s[6:7], 13
	v_writelane_b32 v254, s8, 47
	s_lshl_b64 s[6:7], s[6:7], 12
	s_add_u32 s2, s2, s76
	v_writelane_b32 v254, s9, 48
	v_writelane_b32 v254, s0, 49
	s_addc_u32 s3, s3, s77
	s_ashr_i32 s85, s84, 31
	v_writelane_b32 v254, s1, 50
	v_writelane_b32 v254, s6, 51
	v_add_u32_e32 v176, v0, v1
	s_add_i32 s0, s84, s5
	v_writelane_b32 v254, s7, 52
	v_writelane_b32 v254, s2, 53
	s_lshl_b64 s[6:7], s[84:85], 12
	v_writelane_b32 v253, s6, 8
	v_writelane_b32 v254, s3, 54
	v_writelane_b32 v254, s5, 55
	v_writelane_b32 v254, s0, 56
	s_lshl_b32 s2, s33, 17
	v_mbcnt_lo_u32_b32 v0, -1, 0
	s_lshl_b64 s[4:5], s[84:85], 11
	v_writelane_b32 v253, s7, 9
	s_movk_i32 s85, 0x90
	s_movk_i32 s6, 0x4400
	s_movk_i32 s7, 0x110
	s_movk_i32 s8, 0xf7
	s_movk_i32 s9, 0x101
	s_mov_b32 s0, 0x3fd744fd
	s_lshl_b32 s27, s2, 1
	v_mbcnt_hi_u32_b32 v188, -1, v0
	v_writelane_b32 v254, s97, 57
	s_branch .LBB0_230

.LBB0_633:
	v_readlane_b32 s2, v254, 37
	v_readlane_b32 s3, v254, 38
	v_readlane_b32 s60, v255, 0
	s_and_b64 vcc, exec, s[2:3]
	v_readlane_b32 s97, v254, 57
	s_mov_b64 s[76:77], s[34:35]
	v_readlane_b32 s61, v255, 1
	s_cbranch_vccz .LBB0_641
	v_readlane_b32 s98, v253, 0
	v_readlane_b32 s99, v254, 32
	s_cmpk_eq_u32 s99, 0x100
	s_movk_i32 s99, 0x2000
	s_cselect_b32 s99, 0x2000, s99
	s_cmpk_lt_u32 s98, 0x100
	s_cselect_b32 s98, 0x2000, s99
	v_readlane_b32 s2, v254, 60
	v_readlane_b32 s3, v254, 61
	s_lshl_b32 s2, s2, 25
	v_readlane_b32 s3, v254, 43
	v_readlane_b32 s38, v254, 33
	s_waitcnt lgkmcnt(0)
	v_readlane_b32 s99, v254, 32
	v_readlane_b32 s100, v254, 44
	v_and_b32_e32 v0, 63, v133
	v_lshrrev_b32_e32 v1, 6, v133
	v_mul_u32_u24_e32 v2, 0x4200, v1
	v_lshl_add_u32 v200, v0, 1, v2
	v_lshl_add_u32 v201, v0, 4, v2
	v_lshlrev_b32_e32 v3, 13, v1
	v_lshl_add_u32 v202, v0, 4, v3
	v_mov_b32_e32 v203, 0
	v_lshrrev_b32_e32 v4, 3, v133
	v_and_b32_e32 v4, 3, v4
	v_lshlrev_b32_e32 v4, 21, v4
	v_lshrrev_b32_e32 v5, 5, v133
	v_lshl_add_u32 v4, v5, 7, v4
	v_and_b32_e32 v5, 7, v133
	v_lshl_add_u32 v204, v5, 4, v4
	v_mov_b32_e32 v205, 0
	s_cmpk_gt_i32 s38, 0xfff
	s_cselect_b32 s42, s54, s52
	s_cselect_b32 s43, s55, s53
	s_mov_b32 s46, 0x2c00000
	s_cselect_b32 s46, 0xac00000, s46
	s_mov_b32 s44, 0x42800000
	s_cselect_b32 s44, 0x41500000, s44
	s_and_b32 s39, s3, 0x1ffe000
	s_or_b32 s80, s39, s2
	s_lshl_b32 s39, s80, 2
	s_add_u32 s42, s42, s39
	s_addc_u32 s43, s43, 0
	v_lshl_add_u64 v[0:1], s[42:43], 0, v[202:203]
	s_add_u32 s42, s42, 0x1000
	s_addc_u32 s43, s43, 0
	v_lshl_add_u64 v[2:3], s[42:43], 0, v[202:203]
	global_load_dwordx4 v[142:145], v[0:1], off
	global_load_dwordx4 v[146:149], v[0:1], off offset:1024
	global_load_dwordx4 v[150:153], v[0:1], off offset:2048
	global_load_dwordx4 v[154:157], v[0:1], off offset:3072
	global_load_dwordx4 v[158:161], v[2:3], off
	global_load_dwordx4 v[162:165], v[2:3], off offset:1024
	global_load_dwordx4 v[166:169], v[2:3], off offset:2048
	global_load_dwordx4 v[170:173], v[2:3], off offset:3072
	s_lshr_b32 s39, s80, 1
	s_and_b32 s39, s39, 0x3800000
	s_lshr_b32 s47, s80, 3
	s_and_b32 s47, s47, 0x1fff80
	s_or_b32 s39, s39, s47
	s_add_u32 s46, s46, s39
	s_add_u32 s46, s58, s46
	s_addc_u32 s47, s59, 0
	v_lshl_add_u64 v[240:241], s[46:47], 0, v[204:205]
	v_mov_b32_e32 v8, s44
